# P6 row-scale pre-pass moved behind the GEMM prologue's staged loads; conv phase entry no longer drains the up-projection stores (lgkmcnt-only wait before the barrier)
# speedup vs baseline: 1.0078x; 1.0003x over previous
; #define LAS __attribute__((address_space(3)))
; DI void conv_item(LAS unsigned char* lds, int item, const bf16_t* P, const float* cw, const float* cb, const float* lng, const float* lnb, bf16_t* MIX) {
;     LAS float* U = (LAS float*)lds;
;     const int tid = threadIdx.x, lane = tid & 63, wid = tid >> 6;
;     const int tt0 = (item >> 3) * 128, g = item & 7, cbase = g * 128;
;     const int bstart = tt0 & ~(SEQ - 1);
;     {
;         u32x4 vv[5], gv[5];
; #pragma unroll
;         for (int j = 0; j < 5; ++j) {
;             const int id = tid + 512 * j, row = id >> 4, c8 = (id & 15) * 8, tt = tt0 - 30 + row;
;             vv[j] = (u32x4){0u, 0u, 0u, 0u}; gv[j] = vv[j];
;             if (id < 158 * 16 && tt >= bstart) { vv[j] = *(const u32x4*)(P + (size_t)tt * LDP + cbase + c8); gv[j] = *(const u32x4*)(P + (size_t)tt * LDP + 1024 + cbase + c8); }
; __global__ void __launch_bounds__(512, 2) fwd_kernel(Args a) {
;     ...
;     if (IN(3)) {
;         __syncthreads();
;         for (int it = bx; it < 512; it += G) conv_item(lds, it, PB, a.in[3], a.in[4], a.in[5], a.in[6], MIX);
.LBB0_514:
	s_cmp_lt_i32 s84, 4
	s_cselect_b64 s[0:1], -1, 0
	s_cmp_gt_i32 s85, 3
	s_cselect_b64 s[4:5], -1, 0
	s_and_b64 s[10:11], s[0:1], s[4:5]
	s_andn2_b64 vcc, exec, s[10:11]
	s_cbranch_vccnz .LBB0_536
	s_cmpk_gt_i32 s2, 0x1ff
	s_waitcnt lgkmcnt(0)
	s_barrier
	s_cbranch_scc1 .LBB0_532
	v_lshlrev_b32_e32 v0, 3, v253
	v_add_u32_e32 v1, 0x200, v253
	v_and_b32_e32 v0, 0x78, v0
	v_lshrrev_b32_e32 v69, 4, v1
	v_lshlrev_b32_e32 v1, 5, v1
	v_or_b32_e32 v2, 0x400, v253
	v_lshl_add_u32 v5, v0, 2, 0
	v_and_b32_e32 v1, 0xfe00, v1
	v_add_u32_e32 v74, v5, v1
	v_lshlrev_b32_e32 v1, 5, v2
	v_add_u32_e32 v3, 0x600, v253
	v_and_b32_e32 v1, 0xfe00, v1
	v_add_u32_e32 v75, v5, v1
	v_lshlrev_b32_e32 v1, 5, v3
	v_or_b32_e32 v4, 0x800, v253
	v_and_b32_e32 v1, 0x1fe00, v1
	v_add_u32_e32 v76, v5, v1
	v_lshlrev_b32_e32 v1, 5, v4
	v_and_b32_e32 v1, 0x17e00, v1
	v_add_u32_e32 v77, v5, v1
	v_and_b32_e32 v78, 0x7f, v253
	v_lshlrev_b32_e32 v1, 7, v253
	v_lshrrev_b32_e32 v70, 4, v2
	v_and_b32_e32 v1, 0x1c000, v1
	v_lshlrev_b32_e32 v2, 2, v78
	v_lshrrev_b32_e32 v71, 4, v3
	v_add3_u32 v79, 0, v1, v2
	v_bfe_u32 v1, v253, 4, 2
	v_lshrrev_b32_e32 v3, 2, v253
	s_movk_i32 s8, 0xf0
	s_movk_i32 s0, 0x3df
	s_movk_i32 s3, 0x3e0
	v_and_or_b32 v80, v3, s8, v1
	v_mbcnt_lo_u32_b32 v1, -1, 0
	v_cmp_lt_u32_e32 vcc, s0, v253
	s_movk_i32 s0, 0x9df
	v_cmp_gt_u32_e64 s[4:5], s3, v253
	s_movk_i32 s3, 0x9e0
	v_mbcnt_hi_u32_b32 v1, -1, v1
	v_lshrrev_b32_e32 v72, 4, v4
	v_cmp_lt_u32_e64 s[0:1], s0, v4
	v_cmp_gt_u32_e64 s[6:7], s3, v4
	v_and_b32_e32 v4, 64, v1
	v_xor_b32_e32 v3, 1, v1
	v_add_u32_e32 v4, 64, v4
	v_cmp_lt_i32_e64 s[8:9], v3, v4
	v_lshlrev_b32_e32 v2, 2, v253
	v_and_b32_e32 v2, 60, v2
	v_cndmask_b32_e64 v3, v1, v3, s[8:9]
	v_lshlrev_b32_e32 v81, 2, v3
	v_xor_b32_e32 v3, 2, v1
	v_cmp_lt_i32_e64 s[8:9], v3, v4
	v_lshlrev_b32_e32 v40, 2, v2
	v_or_b32_e32 v86, 4, v80
	v_cndmask_b32_e64 v3, v1, v3, s[8:9]
	v_lshlrev_b32_e32 v82, 2, v3
	v_xor_b32_e32 v3, 4, v1
	v_cmp_lt_i32_e64 s[8:9], v3, v4
	v_or_b32_e32 v88, 8, v80
	v_lshlrev_b32_e32 v6, 5, v253
	v_cndmask_b32_e64 v3, v1, v3, s[8:9]
	v_lshlrev_b32_e32 v83, 2, v3
	v_xor_b32_e32 v3, 8, v1
	v_cmp_lt_i32_e64 s[8:9], v3, v4
	v_or_b32_e32 v90, 12, v80
	v_mov_b32_e32 v41, 0
	v_cndmask_b32_e64 v1, v1, v3, s[8:9]
	v_lshlrev_b32_e32 v84, 2, v1
	v_lshlrev_b32_e32 v1, 9, v80
	v_add3_u32 v85, 0, v1, v40
	v_lshlrev_b32_e32 v1, 9, v86
	v_add3_u32 v87, 0, v1, v40
	v_lshlrev_b32_e32 v1, 9, v88
	v_and_b32_e32 v6, 0x7e00, v6
	v_add3_u32 v89, 0, v1, v40
	v_lshlrev_b32_e32 v1, 9, v90
	v_lshrrev_b32_e32 v68, 4, v253
	s_mov_b32 s13, 0
	v_add_u32_e32 v73, v5, v6
	s_mov_b32 s3, 0x1c000
	v_add3_u32 v91, 0, v1, v40
	v_lshl_add_u64 v[42:43], s[18:19], 0, v[40:41]
	v_lshl_add_u64 v[44:45], s[20:21], 0, v[40:41]
	s_lshl_b32 s21, s2, 4
	s_lshl_b32 s23, s58, 4
	s_lshl_b32 s28, s2, 7
	s_lshl_b32 s29, s58, 7
	s_movk_i32 s30, 0x2880
	s_xor_b64 s[8:9], vcc, -1
	s_xor_b64 s[0:1], s[0:1], -1
	s_movk_i32 s31, 0x1000
	v_lshlrev_b32_e32 v46, 1, v2
	s_mov_b64 s[18:19], 0x1000
	s_brev_b32 s20, 60
	s_mov_b32 s22, 0x358637bd
	s_mov_b32 s34, 0x800000
	v_lshlrev_b32_e32 v48, 1, v0
	s_mov_b32 s35, s2
	s_branch .LBB0_518

; #define PG8_STAGE(bufoff, gbase, voff) do { _Pragma("unroll") for (int _i = 0; _i < 2; ++_i) \
;         __builtin_amdgcn_global_load_lds((const unsigned*)((const char*)(gbase) + (voff)[_i]), (LAS unsigned*)(lds + (bufoff) + ldsw + _i * 8192), 16, 0, 0); } while (0)
; #define PG8_BAR __builtin_amdgcn_s_barrier()
; template <class Epi, class Sched>
; __device__ __forceinline__ void gemm_phase(LAS unsigned char* lds, const Gemm g, const Sched& S, const Epi& E) {
;     ...
;     for (int i = 0; i < 2; ++i) { int R, C; stage_rc(tid * 16 + i * 8192, R, C); const int Rb = Epi::PERM ? ((R & ~31) + perm32(R & 31)) : R;
;         voffA[i] = (unsigned)(R * g.lda + C) * 2u; voffB[i] = (unsigned)(Rb * g.ldb + C) * 2u; }
;     const size_t kstep = (size_t)(BK * 2);
;     const size_t hsA = (size_t)HALF * g.lda * 2, hsB = (size_t)HALF * g.ldb * 2;
;     const size_t tsA = 2 * hsA, tsB = 2 * hsB;
;     const unsigned ldsw = (unsigned)wid * 1024u;
;     const int aoff = lds_byte(wr * 64 + fr, fq * 8), boff = lds_byte(wc * 32 + fr, fq * 8);
;     ...
;     Unit cur, nxt; int ui = 0;
;     if (!S.next(0, cur)) return;
;     f32x4 acc[2][2][4][2];
; #pragma unroll
;     for (int a = 0; a < 2; ++a)
; #pragma unroll
;         for (int b = 0; b < 2; ++b)
; #pragma unroll
;             for (int m = 0; m < 4; ++m)
; #pragma unroll
;                 for (int n = 0; n < 2; ++n) acc[a][b][m][n] = (f32x4){0.f, 0.f, 0.f, 0.f};
;     bf16x8 At[4][2], B0[2][2], B1[2][2];
;     const char* cA = (const char*)g.A + (size_t)cur.pm * tsA; const char* cB = (const char*)g.Bt + (size_t)cur.pn * tsB;
;     PG8_STAGE(PG8_SB(0, 0), cB, voffB); PG8_STAGE(PG8_SB(0, 1), cB + hsB, voffB); PG8_STAGE(PG8_SA(0, 0), cA, voffA); PG8_STAGE(PG8_SA(0, 1), cA + hsA, voffA);
;     if (wr == 1) PG8_BAR;
;     PG8_WAIT_V(2); PG8_BAR;
;     PG8_STAGE(PG8_SB(1, 0), cB + kstep, voffB); PG8_STAGE(PG8_SA(1, 0), cA + kstep, voffA); PG8_STAGE(PG8_SB(1, 1), cB + hsB + kstep, voffB);
;     PG8_WAIT_V(6); PG8_BAR;
;     DI void operator()(const f32x4 (&acc)[2][2][4][2], const Unit& u, int wr, int wc, int fr, int fq) const {
;     ...
; #pragma unroll
;         for (int i = 0; i < 8; ++i) rsv[i] = ssq8(ssq + (size_t)(rbase + (i >> 2) * 128 + (i & 3) * 16) * 32 + 8 * fq);
; #pragma unroll
;         for (int i = 0; i < 8; ++i) { float sq = rsv[i]; sq += __shfl_xor(sq, 16); sq += __shfl_xor(sq, 32); rsv[i] = rsqrtf(sq * (1.f / 2048.f) + EPS_); }
.Lp6_nomap0:
	v_lshrrev_b32_e32 v2, 1, v253
	v_and_b32_e32 v11, 24, v2
	v_lshrrev_b32_e32 v2, 5, v253
	v_and_b32_e32 v2, 4, v2
	v_bfe_u32 v3, v253, 2, 2
	v_lshlrev_b32_e32 v0, 4, v253
	s_waitcnt lgkmcnt(0)
	v_and_b32_e32 v1, 32, v253
	v_bfe_u32 v10, v253, 2, 4
	v_or3_b32 v2, v2, v3, v11
	v_lshrrev_b32_e32 v3, 3, v253
	s_movk_i32 s5, 0x70
	v_bitop3_b32 v8, v0, v1, 48 bitop3:0x6c
	v_and_b32_e32 v9, 64, v253
	v_and_or_b32 v4, v3, s5, v10
	s_movk_i32 s5, 0x60
	v_add_u32_e32 v12, 0x2000, v0
	v_or_b32_e32 v1, v8, v9
	v_and_or_b32 v3, v3, s5, v2
	v_lshrrev_b32_e32 v0, 7, v12
	s_movk_i32 s5, 0xf0
	s_add_u32 s3, s82, 0x2480000
	s_waitcnt vmcnt(0)
	v_lshl_or_b32 v130, v3, 12, v1
	v_and_or_b32 v3, v0, s5, v10
	s_movk_i32 s5, 0xe0
	s_addc_u32 s46, s83, 0
	v_and_or_b32 v0, v0, s5, v2
	s_lshr_b32 s5, s20, 6
	s_ashr_i32 s7, s6, 31
	s_ashr_i32 s9, s8, 31
	s_lshr_b32 s4, s20, 8
	s_lshl_b32 s47, s5, 10
	s_lshl_b64 s[10:11], s[6:7], 20
	s_lshl_b64 s[14:15], s[8:9], 20
	s_add_u32 s40, s3, s14
	s_addc_u32 s41, s46, s15
	s_add_i32 s48, s47, 0
	s_add_i32 m0, s48, 0x10000
	v_lshl_or_b32 v134, v0, 12, v1
	global_load_lds_dwordx4 v130, s[40:41]
	s_add_i32 m0, s48, 0x12000
	s_add_u32 s14, s40, 0x80000
	global_load_lds_dwordx4 v134, s[40:41]
	s_addc_u32 s15, s41, 0
	s_add_i32 m0, s48, 0x14000
	v_lshl_or_b32 v128, v4, 12, v1
	global_load_lds_dwordx4 v130, s[14:15]
	s_add_i32 m0, s48, 0x16000
	s_add_u32 s10, s62, s10
	s_addc_u32 s11, s63, s11
	s_add_i32 s49, s48, 0x2000
	global_load_lds_dwordx4 v134, s[14:15]
	s_mov_b32 m0, s48
	s_add_u32 s14, s10, 0x80000
	v_lshl_or_b32 v132, v3, 12, v1
	global_load_lds_dwordx4 v128, s[10:11]
	s_mov_b32 m0, s49
	s_addc_u32 s15, s11, 0
	s_add_i32 s50, s48, 0x4000
	global_load_lds_dwordx4 v132, s[10:11]
	s_mov_b32 m0, s50
	s_add_i32 s51, s48, 0x6000
	global_load_lds_dwordx4 v128, s[14:15]
	s_mov_b32 m0, s51
	v_mov_b32_e32 v137, 0
	global_load_lds_dwordx4 v132, s[14:15]
	v_mov_b32_e32 v131, v137
	v_mov_b32_e32 v135, v137
	v_mov_b32_e32 v129, v137
	v_mov_b32_e32 v133, v137
	s_cmp_eq_u32 s4, 1
	s_mov_b32 s52, 0
	v_lshl_add_u64 v[6:7], s[40:41], 0, v[130:131]
	v_lshl_add_u64 v[4:5], s[40:41], 0, v[134:135]
	v_lshl_add_u64 v[0:1], s[10:11], 0, v[128:129]
	s_cselect_b64 s[14:15], -1, 0
	s_cmp_lg_u32 s4, 1
	v_lshl_add_u64 v[2:3], s[10:11], 0, v[132:133]
	s_cbranch_scc1 .LBB0_786
	s_barrier
.LBB0_786:
	s_add_u32 s16, s82, 0x8c80000
	s_addc_u32 s17, s83, 0
	s_lshl_b32 s53, s4, 6
	s_lshl_b32 s7, s4, 13
	s_lshl_b32 s4, s5, 5
	s_mov_b64 s[18:19], 0x80
	s_and_b32 s9, s4, 0x60
	s_add_i32 m0, s48, 0x18000
	v_lshl_add_u64 v[6:7], v[6:7], 0, s[18:19]
	s_lshl_b32 s21, s9, 7
	s_waitcnt vmcnt(2)
	s_barrier
	global_load_lds_dwordx4 v[6:7], off
	v_lshl_add_u64 v[4:5], v[4:5], 0, s[18:19]
	s_add_i32 m0, s48, 0x1a000
	s_add_i32 s54, s48, 0x8000
	s_add_i32 s55, s48, 0xa000
	global_load_lds_dwordx4 v[4:5], off
	v_lshl_add_u64 v[0:1], v[0:1], 0, s[18:19]
	s_mov_b32 m0, s54
	s_add_u32 s4, s40, 0x80080
	global_load_lds_dwordx4 v[0:1], off
	v_lshl_add_u64 v[0:1], v[2:3], 0, s[18:19]
	s_mov_b32 m0, s55
	s_addc_u32 s5, s41, 0
	global_load_lds_dwordx4 v[0:1], off
	s_add_i32 m0, s48, 0x1c000
	v_lshl_add_u64 v[0:1], s[4:5], 0, v[130:131]
	global_load_lds_dwordx4 v[0:1], off
	v_lshl_add_u64 v[0:1], s[4:5], 0, v[134:135]
	s_add_i32 m0, s48, 0x1e000
	v_and_b32_e32 v138, 15, v253
	global_load_lds_dwordx4 v[0:1], off
	v_lshlrev_b32_e32 v0, 1, v11
	v_lshlrev_b32_e32 v2, 2, v253
	v_lshlrev_b32_e32 v3, 6, v253
	s_movk_i32 s4, 0x3c0
	v_lshl_or_b32 v1, v138, 6, v0
	v_and_b32_e32 v2, 32, v2
	v_and_or_b32 v0, v3, s4, v0
	v_bitop3_b32 v139, s21, v0, v2 bitop3:0xf6
	v_lshlrev_b32_e32 v0, 9, v253
	v_bitop3_b32 v1, v1, s7, v2 bitop3:0xde
	v_and_b32_e32 v0, 0x70000, v0
	v_lshlrev_b32_e32 v2, 12, v10
	v_or3_b32 v0, v8, v0, v2
	v_add_u32_e32 v142, v0, v9
	v_lshlrev_b32_e32 v0, 5, v12
	v_and_b32_e32 v0, 0xf0000, v0
	s_waitcnt vmcnt(6)
	s_cmpk_lt_u32 s20, 0x100
	v_lshlrev_b32_e32 v136, 2, v11
	v_or3_b32 v0, v8, v0, v2
	s_cselect_b64 s[20:21], -1, 0
	v_lshl_add_u64 v[140:141], s[0:1], 0, v[136:137]
	v_add_u32_e32 v144, v0, v9
	s_add_i32 s1, 0, 0x10000
	s_add_i32 s67, 0, 0x14000
	v_mbcnt_lo_u32_b32 v0, -1, 0
	v_or_b32_e32 v151, s9, v11
	s_ashr_i32 s64, s58, 31
	s_mov_b32 s65, s58
	s_ashr_i32 s66, s2, 31
	v_mov_b32_e32 v143, v137
	v_mov_b32_e32 v145, v137
	v_mov_b64_e32 v[146:147], 0x400
	v_mov_b64_e32 v[148:149], 0x3ff
	v_add_u32_e32 v182, s1, v139
	v_add_u32_e32 v183, s67, v139
	v_add_u32_e32 v184, 0, v1
	v_mbcnt_hi_u32_b32 v185, -1, v0
	s_mov_b32 s0, 0x3a000000
	s_mov_b32 s68, 0x800000
	v_lshlrev_b32_e32 v136, 1, v138
	s_mov_b64 s[22:23], 0x48000
	s_mov_b64 s[26:27], 0x50000
	s_mov_b64 s[28:29], 0x58000
	v_mov_b32_e32 v150, 0x358637bd
	v_cmp_gt_u32_e32 vcc, 0x100, v253
	s_and_saveexec_b64 s[98:99], vcc
	s_cbranch_execz .Lrt6_skip
	s_lshl_b32 s100, s6, 15
	s_add_u32 s100, s100, s82
	s_addc_u32 s101, s83, 0
	s_add_u32 s100, s100, 0x100000
	s_addc_u32 s101, s101, 0
	v_lshlrev_b32_e32 v0, 7, v253
	global_load_dwordx4 v[4:7], v0, s[100:101]
	global_load_dwordx4 v[8:11], v0, s[100:101] offset:16
	global_load_dwordx4 v[12:15], v0, s[100:101] offset:32
	global_load_dwordx4 v[16:19], v0, s[100:101] offset:48
	global_load_dwordx4 v[20:23], v0, s[100:101] offset:64
	global_load_dwordx4 v[24:27], v0, s[100:101] offset:80
	global_load_dwordx4 v[28:31], v0, s[100:101] offset:96
	global_load_dwordx4 v[32:35], v0, s[100:101] offset:112
	s_waitcnt vmcnt(0)
	v_add_f32_e32 v36, v4, v5
	v_add_f32_e32 v37, v6, v7
	v_add_f32_e32 v36, v36, v37
	v_add_f32_e32 v37, v8, v9
	v_add_f32_e32 v38, v10, v11
	v_add_f32_e32 v37, v37, v38
	v_add_f32_e32 v40, v36, v37
	v_add_f32_e32 v36, v12, v13
	v_add_f32_e32 v37, v14, v15
	v_add_f32_e32 v36, v36, v37
	v_add_f32_e32 v37, v16, v17
	v_add_f32_e32 v38, v18, v19
	v_add_f32_e32 v37, v37, v38
	v_add_f32_e32 v41, v36, v37
	v_add_f32_e32 v36, v20, v21
	v_add_f32_e32 v37, v22, v23
	v_add_f32_e32 v36, v36, v37
	v_add_f32_e32 v37, v24, v25
	v_add_f32_e32 v38, v26, v27
	v_add_f32_e32 v37, v37, v38
	v_add_f32_e32 v42, v36, v37
	v_add_f32_e32 v36, v28, v29
	v_add_f32_e32 v37, v30, v31
	v_add_f32_e32 v36, v36, v37
	v_add_f32_e32 v37, v32, v33
	v_add_f32_e32 v38, v34, v35
	v_add_f32_e32 v37, v37, v38
	v_add_f32_e32 v43, v36, v37
	v_add_f32_e32 v36, v40, v41
	v_add_f32_e32 v37, v42, v43
	v_add_f32_e32 v36, v36, v37
	v_lshlrev_b32_e32 v1, 2, v253
	v_add_u32_e32 v1, 0x20400, v1
	ds_write_b32 v1, v36
.Lrt6_skip:
	s_or_b64 exec, exec, s[98:99]
	s_waitcnt lgkmcnt(0)
	s_barrier
	s_branch .LBB0_789
